# cost-weighted VALU spacing in the last PV group of the first half (exp into v175 and the vcc test moved into earlier gaps, pad removed), with back-edge rotation
# speedup vs baseline: 1.0007x; 1.0007x over previous
.LBB0_433:
	ds_read_b128 v[64:67], v166 offset:49152
	ds_read_b128 v[68:71], v166 offset:57344
	ds_read_b128 v[176:179], v167 offset:49152
	ds_read_b128 v[198:201], v167 offset:57344
	ds_read_b128 v[202:205], v168 offset:49152
	ds_read_b128 v[210:213], v168 offset:57344
	s_add_u32 m0, s86, 0x8000
	s_nop 0
	global_load_lds_dwordx4 v247, s[82:83]
	s_add_u32 m0, s86, 0x8400
	s_nop 0
	global_load_lds_dwordx4 v248, s[82:83]
	s_add_u32 s82, s82, 0x8000
	s_addc_u32 s83, s83, 0
	v_exp_f32_e32 v142, v142
	v_exp_f32_e32 v143, v143
	v_exp_f32_e32 v180, v140
	v_exp_f32_e32 v181, v141
	v_exp_f32_e32 v206, v138
	v_exp_f32_e32 v207, v135
	v_exp_f32_e32 v148, v148
	v_exp_f32_e32 v149, v149
	v_exp_f32_e32 v209, v146
	s_waitcnt lgkmcnt(5)
	v_mfma_f32_32x32x16_bf16 v[80:95], v[64:67], v[124:127], 0
	s_waitcnt lgkmcnt(4)
	v_mfma_f32_32x32x16_bf16 v[64:79], v[68:71], v[124:127], 0
	v_cvt_pk_bf16_f32 v135, v192, v193
	v_cvt_pk_bf16_f32 v138, v182, v183
	v_cvt_pk_bf16_f32 v140, v185, v187
	v_cvt_pk_bf16_f32 v141, v188, v189
	s_nop 0
	s_waitcnt lgkmcnt(3)
	v_mfma_f32_32x32x16_bf16 v[80:95], v[176:179], v[120:123], v[80:95]
	ds_read_b128 v[176:179], v169 offset:49152
	ds_read_b128 v[214:217], v169 offset:57344
	ds_read_b128 v[218:221], v170 offset:49152
	ds_read_b128 v[222:225], v170 offset:57344
	ds_read_b128 v[226:229], v171 offset:49152
	ds_read_b128 v[230:233], v171 offset:57344
	ds_read_b128 v[234:237], v172 offset:49152
	ds_read_b128 v[238:241], v172 offset:57344
	s_waitcnt lgkmcnt(10)
	v_mfma_f32_32x32x16_bf16 v[64:79], v[198:201], v[120:123], v[64:79]
	ds_read_b128 v[198:201], v173 offset:49152
	ds_read_b128 v[242:245], v173 offset:57344
	s_waitcnt lgkmcnt(11)
	v_mfma_f32_32x32x16_bf16 v[80:95], v[202:205], v[112:115], v[80:95]
	v_exp_f32_e32 v205, v134
	v_add_f32_e32 v134, v191, v190
	v_add_f32_e32 v134, v192, v134
	v_add_f32_e32 v134, v193, v134
	v_add_f32_e32 v134, v194, v134
	v_add_f32_e32 v134, v196, v134
	s_waitcnt lgkmcnt(10)
	v_mfma_f32_32x32x16_bf16 v[64:79], v[210:213], v[112:115], v[64:79]
	v_add_f32_e32 v134, v195, v134
	v_add_f32_e32 v134, v197, v134
	v_add_f32_e32 v134, v182, v134
	v_add_f32_e32 v134, v183, v134
	v_add_f32_e32 v134, v184, v134
	v_add_f32_e32 v134, v186, v134
	v_add_f32_e32 v134, v185, v134
	s_waitcnt lgkmcnt(9)
	v_mfma_f32_32x32x16_bf16 v[80:95], v[176:179], v[116:119], v[80:95]
	v_add_f32_e32 v134, v187, v134
	v_add_f32_e32 v134, v188, v134
	v_add_f32_e32 v134, v189, v134
	v_add_f32_e32 v134, v142, v134
	v_exp_f32_e32 v202, v139
	v_add_f32_e32 v134, v143, v134
	v_exp_f32_e32 v203, v136
	s_waitcnt lgkmcnt(8)
	v_mfma_f32_32x32x16_bf16 v[64:79], v[214:217], v[116:119], v[64:79]
	v_add_f32_e32 v134, v180, v134
	v_exp_f32_e32 v204, v137
	v_add_f32_e32 v134, v181, v134
	v_add_f32_e32 v134, v206, v134
	v_add_f32_e32 v134, v202, v134
	v_add_f32_e32 v134, v203, v134
	v_add_f32_e32 v134, v204, v134
	s_waitcnt lgkmcnt(7)
	v_mfma_f32_32x32x16_bf16 v[80:95], v[218:221], v[108:111], v[80:95]
	v_add_f32_e32 v134, v205, v134
	v_exp_f32_e32 v210, v147
	v_add_f32_e32 v134, v207, v134
	v_exp_f32_e32 v211, v144
	v_add_f32_e32 v134, v148, v134
	v_exp_f32_e32 v212, v145
	v_add_f32_e32 v134, v149, v134
	s_waitcnt lgkmcnt(6)
	v_mfma_f32_32x32x16_bf16 v[64:79], v[222:225], v[108:111], v[64:79]
	v_add_f32_e32 v134, v209, v134
	v_add_f32_e32 v134, v210, v134
	v_add_f32_e32 v134, v211, v134
	v_add_f32_e32 v176, v212, v134
	v_cvt_pk_bf16_f32 v134, v190, v191
	v_cvt_pk_bf16_f32 v136, v194, v196
	s_waitcnt lgkmcnt(5)
	v_mfma_f32_32x32x16_bf16 v[80:95], v[226:229], v[104:107], v[80:95]
	v_cvt_pk_bf16_f32 v137, v195, v197
	v_cvt_pk_bf16_f32 v139, v184, v186
	v_cvt_pk_bf16_f32 v142, v142, v143
	s_waitcnt lgkmcnt(4)
	v_mfma_f32_32x32x16_bf16 v[64:79], v[230:233], v[104:107], v[64:79]
	ds_read_b64_tr_b16 v[218:219], v161 offset:0
	ds_read_b64_tr_b16 v[220:221], v161 offset:2048
	ds_read_b64_tr_b16 v[222:223], v161 offset:4096
	ds_read_b64_tr_b16 v[224:225], v161 offset:6144
	ds_read_b64_tr_b16 v[226:227], v161 offset:8192
	ds_read_b64_tr_b16 v[228:229], v161 offset:10240
	ds_read_b64_tr_b16 v[230:231], v161 offset:12288
	ds_read_b64_tr_b16 v[232:233], v161 offset:14336
	v_cvt_pk_bf16_f32 v143, v180, v181
	v_cvt_pk_bf16_f32 v144, v206, v202
	v_cvt_pk_bf16_f32 v145, v203, v204
	v_cvt_pk_bf16_f32 v146, v205, v207
	v_cvt_pk_bf16_f32 v147, v148, v149
	v_cvt_pk_bf16_f32 v148, v209, v210
	v_cvt_pk_bf16_f32 v149, v211, v212
	s_waitcnt lgkmcnt(11)
	v_mfma_f32_32x32x16_bf16 v[80:95], v[234:237], v[100:103], v[80:95]
	s_waitcnt lgkmcnt(10)
	v_mfma_f32_32x32x16_bf16 v[64:79], v[238:241], v[100:103], v[64:79]
	s_waitcnt lgkmcnt(9)
	v_mfma_f32_32x32x16_bf16 v[80:95], v[198:201], v[96:99], v[80:95]
	s_waitcnt lgkmcnt(8)
	v_mfma_f32_32x32x16_bf16 v[64:79], v[242:245], v[96:99], v[64:79]
	s_waitcnt lgkmcnt(0)
	s_nop 0
	v_mfma_f32_32x32x16_bf16 v[0:15], v[134:137], v[218:221], v[0:15]
	ds_read_b64_tr_b16 v[196:197], v161 offset:0x200
	ds_read_b64_tr_b16 v[198:199], v161 offset:0xa00
	v_max_f32_e32 v234, v80, v81
	v_max3_f32 v234, v234, v82, v83
	v_max3_f32 v234, v234, v84, v85
	v_max3_f32 v234, v234, v86, v87
	v_max3_f32 v234, v234, v88, v89
	v_mfma_f32_32x32x16_bf16 v[0:15], v[138:141], v[222:225], v[0:15]
	ds_read_b64_tr_b16 v[200:201], v161 offset:0x1200
	ds_read_b64_tr_b16 v[202:203], v161 offset:0x1a00
	v_max3_f32 v234, v234, v90, v91
	v_max3_f32 v234, v234, v92, v93
	v_max3_f32 v234, v234, v94, v95
	v_max3_f32 v234, v234, v64, v65
	v_max3_f32 v234, v234, v66, v67
	v_mfma_f32_32x32x16_bf16 v[0:15], v[142:145], v[226:229], v[0:15]
	ds_read_b64_tr_b16 v[204:205], v161 offset:0x2200
	ds_read_b64_tr_b16 v[206:207], v161 offset:0x2a00
	ds_read_b64_tr_b16 v[214:215], v161 offset:0x3200
	ds_read_b64_tr_b16 v[216:217], v161 offset:0x3a00
	v_max3_f32 v234, v234, v68, v69
	v_max3_f32 v234, v234, v70, v71
	v_max3_f32 v234, v234, v72, v73
	v_max3_f32 v234, v234, v74, v75
	v_max3_f32 v234, v234, v76, v77
	s_waitcnt lgkmcnt(0)
	v_mfma_f32_32x32x16_bf16 v[0:15], v[146:149], v[230:233], v[0:15]
	v_max3_f32 v234, v234, v78, v79
	v_mov_b32_e32 v235, v234
	v_mfma_f32_32x32x16_bf16 v[48:63], v[134:137], v[196:199], v[48:63]
	ds_read_b64_tr_b16 v[196:197], v161 offset:0x400
	ds_read_b64_tr_b16 v[198:199], v161 offset:0xc00
	v_permlane32_swap_b32_e32 v234, v235
	v_max_f32_e32 v234, v234, v235
	v_mfma_f32_32x32x16_bf16 v[48:63], v[138:141], v[200:203], v[48:63]
	ds_read_b64_tr_b16 v[200:201], v161 offset:0x1400
	ds_read_b64_tr_b16 v[202:203], v161 offset:0x1c00
	v_sub_f32_e32 v235, v234, v175
	v_max_f32_e32 v234, v175, v234
	v_sub_f32_e32 v236, v175, v234
	v_mul_f32_e32 v236, 0x3e0293ee, v236
	v_mfma_f32_32x32x16_bf16 v[48:63], v[142:145], v[204:207], v[48:63]
	ds_read_b64_tr_b16 v[204:205], v161 offset:0x2400
	ds_read_b64_tr_b16 v[206:207], v161 offset:0x2c00
	ds_read_b64_tr_b16 v[210:211], v161 offset:0x3400
	ds_read_b64_tr_b16 v[212:213], v161 offset:0x3c00
	v_exp_f32_e32 v236, v236
	v_cmp_ge_f32_e32 vcc, s15, v235
	s_cmp_eq_u64 vcc, exec
	s_cselect_b64 s[8:9], -1, 0
	s_waitcnt lgkmcnt(0)
	v_mfma_f32_32x32x16_bf16 v[48:63], v[146:149], v[214:217], v[48:63]
	v_cndmask_b32_e64 v179, v236, 1.0, s[8:9]
	v_cndmask_b32_e64 v234, v234, v175, s[8:9]
	v_mul_f32_e32 v238, 0xbe0293ee, v234
	v_fmamk_f32 v88, v88, 0x3e0293ee, v238
	v_fmamk_f32 v89, v89, 0x3e0293ee, v238
	v_fmamk_f32 v80, v80, 0x3e0293ee, v238
	v_fmamk_f32 v81, v81, 0x3e0293ee, v238
	v_mfma_f32_32x32x16_bf16 v[32:47], v[134:137], v[196:199], v[32:47]
	ds_read_b64_tr_b16 v[196:197], v161 offset:0x600
	ds_read_b64_tr_b16 v[198:199], v161 offset:0xe00
	v_fmamk_f32 v82, v82, 0x3e0293ee, v238
	v_fmamk_f32 v83, v83, 0x3e0293ee, v238
	v_fmamk_f32 v84, v84, 0x3e0293ee, v238
	v_fmamk_f32 v85, v85, 0x3e0293ee, v238
	v_fmamk_f32 v86, v86, 0x3e0293ee, v238
	v_fmamk_f32 v87, v87, 0x3e0293ee, v238
	v_fmamk_f32 v90, v90, 0x3e0293ee, v238
	v_fmamk_f32 v91, v91, 0x3e0293ee, v238
	v_mfma_f32_32x32x16_bf16 v[32:47], v[138:141], v[200:203], v[32:47]
	ds_read_b64_tr_b16 v[200:201], v161 offset:0x1600
	ds_read_b64_tr_b16 v[202:203], v161 offset:0x1e00
	v_fmamk_f32 v92, v92, 0x3e0293ee, v238
	v_fmamk_f32 v93, v93, 0x3e0293ee, v238
	v_fmamk_f32 v94, v94, 0x3e0293ee, v238
	v_fmamk_f32 v95, v95, 0x3e0293ee, v238
	v_fmamk_f32 v188, v64, 0x3e0293ee, v238
	v_fmamk_f32 v189, v65, 0x3e0293ee, v238
	v_fmamk_f32 v190, v66, 0x3e0293ee, v238
	v_fmamk_f32 v191, v67, 0x3e0293ee, v238
	v_mfma_f32_32x32x16_bf16 v[32:47], v[142:145], v[204:207], v[32:47]
	ds_read_b64_tr_b16 v[204:205], v161 offset:0x2600
	ds_read_b64_tr_b16 v[206:207], v161 offset:0x2e00
	ds_read_b64_tr_b16 v[214:215], v161 offset:0x3600
	ds_read_b64_tr_b16 v[216:217], v161 offset:0x3e00
	v_fmamk_f32 v182, v70, 0x3e0293ee, v238
	v_fmamk_f32 v183, v71, 0x3e0293ee, v238
	v_fmamk_f32 v184, v72, 0x3e0293ee, v238
	v_fmamk_f32 v185, v73, 0x3e0293ee, v238
	v_fmamk_f32 v186, v74, 0x3e0293ee, v238
	v_fmamk_f32 v187, v75, 0x3e0293ee, v238
	s_waitcnt lgkmcnt(0)
	v_mfma_f32_32x32x16_bf16 v[32:47], v[146:149], v[210:213], v[32:47]
	v_fmamk_f32 v192, v68, 0x3e0293ee, v238
	v_fmamk_f32 v181, v69, 0x3e0293ee, v238
	v_fmamk_f32 v180, v76, 0x3e0293ee, v238
	s_waitcnt vmcnt(0)
	s_barrier
	s_add_u32 m0, s86, 0x0
	s_nop 0
	global_load_lds_dwordx4 v249, s[84:85]
	s_add_u32 m0, s86, 0x380
	s_nop 0
	global_load_lds_dwordx4 v249, s[84:85] offset:128
	s_add_u32 s84, s84, 0x8000
	s_addc_u32 s85, s85, 0
	s_add_u32 m0, s86, 0xc000
	s_nop 0
	global_load_lds_dwordx4 v247, s[82:83]
	s_add_u32 m0, s86, 0xc400
	s_nop 0
	global_load_lds_dwordx4 v248, s[82:83]
	s_add_u32 s82, s82, 0x8000
	s_addc_u32 s83, s83, 0
	v_mfma_f32_32x32x16_bf16 v[16:31], v[134:137], v[196:199], v[16:31]
	v_fmamk_f32 v193, v77, 0x3e0293ee, v238
	v_fmamk_f32 v194, v78, 0x3e0293ee, v238
	v_fmamk_f32 v177, v79, 0x3e0293ee, v238
	ds_read_b128 v[64:67], v166 offset:32768
	ds_read_b128 v[68:71], v166 offset:40960
	ds_read_b128 v[196:199], v167 offset:32768
	v_mov_b32_e32 v134, v234
	v_exp_f32_e32 v175, v87
	v_exp_f32_e32 v135, v88
	v_exp_f32_e32 v136, v89
	v_exp_f32_e32 v137, v90
	v_mfma_f32_32x32x16_bf16 v[16:31], v[138:141], v[200:203], v[16:31]
	ds_read_b128 v[200:203], v167 offset:40960
	v_exp_f32_e32 v139, v91
	v_exp_f32_e32 v138, v92
	v_exp_f32_e32 v140, v93
	v_exp_f32_e32 v141, v94
	v_cmp_gt_f32_e32 vcc, 1.0, v179
	v_mfma_f32_32x32x16_bf16 v[16:31], v[142:145], v[204:207], v[16:31]
	ds_read_b128 v[204:207], v168 offset:32768
	ds_read_b128 v[210:213], v168 offset:40960
	v_exp_f32_e32 v142, v95
	v_exp_f32_e32 v143, v80
	v_exp_f32_e32 v144, v81
	v_exp_f32_e32 v145, v82
	v_mfma_f32_32x32x16_bf16 v[16:31], v[146:149], v[214:217], v[16:31]
	v_exp_f32_e32 v146, v83
	v_exp_f32_e32 v147, v84
	v_exp_f32_e32 v149, v85
	v_exp_f32_e32 v148, v86
	s_cbranch_vccz .LBB0_437
	s_and_saveexec_b64 s[2:3], s[6:7]
	ds_write_b32 v158, v179 offset:128
	s_or_b64 exec, exec, s[2:3]
	s_waitcnt lgkmcnt(0)
	v_add_u32_e32 v234, v131, v128
	ds_read_b128 v[218:221], v234 offset:224
	ds_read_b128 v[222:225], v234 offset:192
	ds_read_b128 v[226:229], v234 offset:160
	ds_read_b128 v[230:233], v234 offset:128
	s_waitcnt lgkmcnt(3)
	v_pk_mul_f32 v[12:13], v[12:13], v[218:219]
	s_waitcnt lgkmcnt(2)
	v_pk_mul_f32 v[8:9], v[8:9], v[222:223]
	s_waitcnt lgkmcnt(1)
	v_pk_mul_f32 v[4:5], v[4:5], v[226:227]
	v_pk_mul_f32 v[14:15], v[14:15], v[220:221]
	v_pk_mul_f32 v[10:11], v[10:11], v[224:225]
	v_pk_mul_f32 v[6:7], v[6:7], v[228:229]
	s_waitcnt lgkmcnt(0)
	v_pk_mul_f32 v[2:3], v[2:3], v[232:233]
	v_pk_mul_f32 v[0:1], v[0:1], v[230:231]
	v_pk_mul_f32 v[60:61], v[60:61], v[218:219]
	v_pk_mul_f32 v[56:57], v[56:57], v[222:223]
	v_pk_mul_f32 v[52:53], v[52:53], v[226:227]
	v_pk_mul_f32 v[62:63], v[62:63], v[220:221]
	v_pk_mul_f32 v[58:59], v[58:59], v[224:225]
	v_pk_mul_f32 v[54:55], v[54:55], v[228:229]
	v_pk_mul_f32 v[50:51], v[50:51], v[232:233]
	v_pk_mul_f32 v[48:49], v[48:49], v[230:231]
	v_pk_mul_f32 v[44:45], v[44:45], v[218:219]
	v_pk_mul_f32 v[40:41], v[40:41], v[222:223]
	v_pk_mul_f32 v[36:37], v[36:37], v[226:227]
	v_pk_mul_f32 v[46:47], v[46:47], v[220:221]
	v_pk_mul_f32 v[42:43], v[42:43], v[224:225]
	v_pk_mul_f32 v[38:39], v[38:39], v[228:229]
	v_pk_mul_f32 v[34:35], v[34:35], v[232:233]
	v_pk_mul_f32 v[32:33], v[32:33], v[230:231]
	v_pk_mul_f32 v[28:29], v[28:29], v[218:219]
	v_pk_mul_f32 v[24:25], v[24:25], v[222:223]
	v_pk_mul_f32 v[20:21], v[20:21], v[226:227]
	v_pk_mul_f32 v[30:31], v[30:31], v[220:221]
	v_pk_mul_f32 v[26:27], v[26:27], v[224:225]
	v_pk_mul_f32 v[22:23], v[22:23], v[228:229]
	v_pk_mul_f32 v[18:19], v[18:19], v[232:233]
	v_pk_mul_f32 v[16:17], v[16:17], v[230:231]
